# GEMM loops: per-phase setprio flips deleted, one static s_setprio 1 for waves 0-3 around each K loop
# baseline (speedup 1.0000x reference)
.LBB0_158:
	s_ashr_i32 s19, s18, 31
	s_lshl_b64 s[28:29], s[18:19], 20
	s_add_u32 s28, s21, s28
	s_addc_u32 s29, s23, s29
	s_and_b64 s[30:31], s[2:3], exec
	s_cselect_b32 s19, s29, s37
	s_cselect_b32 s55, s28, s36
	s_ashr_i32 s17, s16, 31
	s_lshl_b64 s[30:31], s[16:17], 20
	s_add_u32 s30, s24, s30
	s_addc_u32 s31, s25, s31
	s_and_b64 s[40:41], s[2:3], exec
	s_cselect_b32 s17, s31, s39
	s_cselect_b32 s56, s30, s38
	s_add_u32 s57, s38, 0x100
	v_mov_b32_e32 v0, 0
	s_addc_u32 s58, s39, 0
	s_mov_b32 s59, -2
	v_mov_b32_e32 v1, v0
	v_mov_b32_e32 v2, v0
	v_mov_b32_e32 v3, v0
	v_mov_b32_e32 v4, v0
	v_mov_b32_e32 v5, v0
	v_mov_b32_e32 v6, v0
	v_mov_b32_e32 v7, v0
	v_mov_b32_e32 v16, v0
	v_mov_b32_e32 v17, v0
	v_mov_b32_e32 v18, v0
	v_mov_b32_e32 v19, v0
	v_mov_b32_e32 v20, v0
	v_mov_b32_e32 v21, v0
	v_mov_b32_e32 v22, v0
	v_mov_b32_e32 v23, v0
	v_mov_b32_e32 v32, v0
	v_mov_b32_e32 v33, v0
	v_mov_b32_e32 v34, v0
	v_mov_b32_e32 v35, v0
	v_mov_b32_e32 v36, v0
	v_mov_b32_e32 v37, v0
	v_mov_b32_e32 v38, v0
	v_mov_b32_e32 v39, v0
	v_mov_b32_e32 v48, v0
	v_mov_b32_e32 v49, v0
	v_mov_b32_e32 v50, v0
	v_mov_b32_e32 v51, v0
	v_mov_b32_e32 v52, v0
	v_mov_b32_e32 v53, v0
	v_mov_b32_e32 v54, v0
	v_mov_b32_e32 v55, v0
	v_mov_b32_e32 v8, v0
	v_mov_b32_e32 v9, v0
	v_mov_b32_e32 v10, v0
	v_mov_b32_e32 v11, v0
	v_mov_b32_e32 v12, v0
	v_mov_b32_e32 v13, v0
	v_mov_b32_e32 v14, v0
	v_mov_b32_e32 v15, v0
	v_mov_b32_e32 v24, v0
	v_mov_b32_e32 v25, v0
	v_mov_b32_e32 v26, v0
	v_mov_b32_e32 v27, v0
	v_mov_b32_e32 v28, v0
	v_mov_b32_e32 v29, v0
	v_mov_b32_e32 v30, v0
	v_mov_b32_e32 v31, v0
	v_mov_b32_e32 v40, v0
	v_mov_b32_e32 v41, v0
	v_mov_b32_e32 v42, v0
	v_mov_b32_e32 v43, v0
	v_mov_b32_e32 v44, v0
	v_mov_b32_e32 v45, v0
	v_mov_b32_e32 v46, v0
	v_mov_b32_e32 v47, v0
	v_mov_b32_e32 v56, v0
	v_mov_b32_e32 v57, v0
	v_mov_b32_e32 v58, v0
	v_mov_b32_e32 v59, v0
	v_mov_b32_e32 v60, v0
	v_mov_b32_e32 v61, v0
	v_mov_b32_e32 v62, v0
	v_mov_b32_e32 v63, v0
	v_mov_b32_e32 v64, v0
	v_mov_b32_e32 v65, v0
	v_mov_b32_e32 v66, v0
	v_mov_b32_e32 v67, v0
	v_mov_b32_e32 v68, v0
	v_mov_b32_e32 v69, v0
	v_mov_b32_e32 v70, v0
	v_mov_b32_e32 v71, v0
	v_mov_b32_e32 v80, v0
	v_mov_b32_e32 v81, v0
	v_mov_b32_e32 v82, v0
	v_mov_b32_e32 v83, v0
	v_mov_b32_e32 v84, v0
	v_mov_b32_e32 v85, v0
	v_mov_b32_e32 v86, v0
	v_mov_b32_e32 v87, v0
	v_mov_b32_e32 v96, v0
	v_mov_b32_e32 v97, v0
	v_mov_b32_e32 v98, v0
	v_mov_b32_e32 v99, v0
	v_mov_b32_e32 v100, v0
	v_mov_b32_e32 v101, v0
	v_mov_b32_e32 v102, v0
	v_mov_b32_e32 v103, v0
	v_mov_b32_e32 v112, v0
	v_mov_b32_e32 v113, v0
	v_mov_b32_e32 v114, v0
	v_mov_b32_e32 v115, v0
	v_mov_b32_e32 v116, v0
	v_mov_b32_e32 v117, v0
	v_mov_b32_e32 v118, v0
	v_mov_b32_e32 v119, v0
	v_mov_b32_e32 v72, v0
	v_mov_b32_e32 v73, v0
	v_mov_b32_e32 v74, v0
	v_mov_b32_e32 v75, v0
	v_mov_b32_e32 v76, v0
	v_mov_b32_e32 v77, v0
	v_mov_b32_e32 v78, v0
	v_mov_b32_e32 v79, v0
	v_mov_b32_e32 v88, v0
	v_mov_b32_e32 v89, v0
	v_mov_b32_e32 v90, v0
	v_mov_b32_e32 v91, v0
	v_mov_b32_e32 v92, v0
	v_mov_b32_e32 v93, v0
	v_mov_b32_e32 v94, v0
	v_mov_b32_e32 v95, v0
	v_mov_b32_e32 v104, v0
	v_mov_b32_e32 v105, v0
	v_mov_b32_e32 v106, v0
	v_mov_b32_e32 v107, v0
	v_mov_b32_e32 v108, v0
	v_mov_b32_e32 v109, v0
	v_mov_b32_e32 v110, v0
	v_mov_b32_e32 v111, v0
	v_mov_b32_e32 v120, v0
	v_mov_b32_e32 v121, v0
	v_mov_b32_e32 v122, v0
	v_mov_b32_e32 v123, v0
	v_mov_b32_e32 v124, v0
	v_mov_b32_e32 v125, v0
	v_mov_b32_e32 v126, v0
	v_mov_b32_e32 v127, v0
	s_cmp_gt_u32 s97, 3
	s_cbranch_scc1 .Lgprio0
	s_setprio 1

.LBB0_247:
	s_add_u32 s63, s46, 0x100
	v_mov_b32_e32 v0, 0
	s_addc_u32 s64, s47, 0
	s_mov_b32 s65, -2
	s_waitcnt lgkmcnt(0)
	v_mov_b32_e32 v1, v0
	v_mov_b32_e32 v2, v0
	v_mov_b32_e32 v3, v0
	v_mov_b32_e32 v4, v0
	v_mov_b32_e32 v5, v0
	v_mov_b32_e32 v6, v0
	v_mov_b32_e32 v7, v0
	v_mov_b32_e32 v16, v0
	v_mov_b32_e32 v17, v0
	v_mov_b32_e32 v18, v0
	v_mov_b32_e32 v19, v0
	v_mov_b32_e32 v20, v0
	v_mov_b32_e32 v21, v0
	v_mov_b32_e32 v22, v0
	v_mov_b32_e32 v23, v0
	v_mov_b32_e32 v32, v0
	v_mov_b32_e32 v33, v0
	v_mov_b32_e32 v34, v0
	v_mov_b32_e32 v35, v0
	v_mov_b32_e32 v36, v0
	v_mov_b32_e32 v37, v0
	v_mov_b32_e32 v38, v0
	v_mov_b32_e32 v39, v0
	v_mov_b32_e32 v48, v0
	v_mov_b32_e32 v49, v0
	v_mov_b32_e32 v50, v0
	v_mov_b32_e32 v51, v0
	v_mov_b32_e32 v52, v0
	v_mov_b32_e32 v53, v0
	v_mov_b32_e32 v54, v0
	v_mov_b32_e32 v55, v0
	v_mov_b32_e32 v8, v0
	v_mov_b32_e32 v9, v0
	v_mov_b32_e32 v10, v0
	v_mov_b32_e32 v11, v0
	v_mov_b32_e32 v12, v0
	v_mov_b32_e32 v13, v0
	v_mov_b32_e32 v14, v0
	v_mov_b32_e32 v15, v0
	v_mov_b32_e32 v24, v0
	v_mov_b32_e32 v25, v0
	v_mov_b32_e32 v26, v0
	v_mov_b32_e32 v27, v0
	v_mov_b32_e32 v28, v0
	v_mov_b32_e32 v29, v0
	v_mov_b32_e32 v30, v0
	v_mov_b32_e32 v31, v0
	v_mov_b32_e32 v40, v0
	v_mov_b32_e32 v41, v0
	v_mov_b32_e32 v42, v0
	v_mov_b32_e32 v43, v0
	v_mov_b32_e32 v44, v0
	v_mov_b32_e32 v45, v0
	v_mov_b32_e32 v46, v0
	v_mov_b32_e32 v47, v0
	v_mov_b32_e32 v56, v0
	v_mov_b32_e32 v57, v0
	v_mov_b32_e32 v58, v0
	v_mov_b32_e32 v59, v0
	v_mov_b32_e32 v60, v0
	v_mov_b32_e32 v61, v0
	v_mov_b32_e32 v62, v0
	v_mov_b32_e32 v63, v0
	v_mov_b32_e32 v64, v0
	v_mov_b32_e32 v65, v0
	v_mov_b32_e32 v66, v0
	v_mov_b32_e32 v67, v0
	v_mov_b32_e32 v68, v0
	v_mov_b32_e32 v69, v0
	v_mov_b32_e32 v70, v0
	v_mov_b32_e32 v71, v0
	v_mov_b32_e32 v80, v0
	v_mov_b32_e32 v81, v0
	v_mov_b32_e32 v82, v0
	v_mov_b32_e32 v83, v0
	v_mov_b32_e32 v84, v0
	v_mov_b32_e32 v85, v0
	v_mov_b32_e32 v86, v0
	v_mov_b32_e32 v87, v0
	v_mov_b32_e32 v96, v0
	v_mov_b32_e32 v97, v0
	v_mov_b32_e32 v98, v0
	v_mov_b32_e32 v99, v0
	v_mov_b32_e32 v100, v0
	v_mov_b32_e32 v101, v0
	v_mov_b32_e32 v102, v0
	v_mov_b32_e32 v103, v0
	v_mov_b32_e32 v112, v0
	v_mov_b32_e32 v113, v0
	v_mov_b32_e32 v114, v0
	v_mov_b32_e32 v115, v0
	v_mov_b32_e32 v116, v0
	v_mov_b32_e32 v117, v0
	v_mov_b32_e32 v118, v0
	v_mov_b32_e32 v119, v0
	v_mov_b32_e32 v72, v0
	v_mov_b32_e32 v73, v0
	v_mov_b32_e32 v74, v0
	v_mov_b32_e32 v75, v0
	v_mov_b32_e32 v76, v0
	v_mov_b32_e32 v77, v0
	v_mov_b32_e32 v78, v0
	v_mov_b32_e32 v79, v0
	v_mov_b32_e32 v88, v0
	v_mov_b32_e32 v89, v0
	v_mov_b32_e32 v90, v0
	v_mov_b32_e32 v91, v0
	v_mov_b32_e32 v92, v0
	v_mov_b32_e32 v93, v0
	v_mov_b32_e32 v94, v0
	v_mov_b32_e32 v95, v0
	v_mov_b32_e32 v104, v0
	v_mov_b32_e32 v105, v0
	v_mov_b32_e32 v106, v0
	v_mov_b32_e32 v107, v0
	v_mov_b32_e32 v108, v0
	v_mov_b32_e32 v109, v0
	v_mov_b32_e32 v110, v0
	v_mov_b32_e32 v111, v0
	v_mov_b32_e32 v120, v0
	v_mov_b32_e32 v121, v0
	v_mov_b32_e32 v122, v0
	v_mov_b32_e32 v123, v0
	v_mov_b32_e32 v124, v0
	v_mov_b32_e32 v125, v0
	v_mov_b32_e32 v126, v0
	v_mov_b32_e32 v127, v0
	s_cmp_gt_u32 s97, 3
	s_cbranch_scc1 .Lgprio1
	s_setprio 1

.LBB0_386:
	s_ashr_i32 s29, s28, 31
	s_lshl_b64 s[30:31], s[28:29], 20
	s_add_u32 s30, s24, s30
	s_addc_u32 s31, s25, s31
	s_and_b64 s[34:35], s[2:3], exec
	s_cselect_b32 s29, s31, s37
	s_cselect_b32 s60, s30, s36
	s_ashr_i32 s19, s18, 31
	s_lshl_b64 s[34:35], s[18:19], 20
	s_add_u32 s34, s26, s34
	s_addc_u32 s35, s27, s35
	s_and_b64 s[40:41], s[2:3], exec
	s_cselect_b32 s19, s35, s39
	s_cselect_b32 s61, s34, s38
	s_add_u32 s62, s38, 0x100
	v_mov_b32_e32 v0, 0
	s_addc_u32 s63, s39, 0
	s_mov_b32 s64, -2
	v_mov_b32_e32 v1, v0
	v_mov_b32_e32 v2, v0
	v_mov_b32_e32 v3, v0
	v_mov_b32_e32 v4, v0
	v_mov_b32_e32 v5, v0
	v_mov_b32_e32 v6, v0
	v_mov_b32_e32 v7, v0
	v_mov_b32_e32 v16, v0
	v_mov_b32_e32 v17, v0
	v_mov_b32_e32 v18, v0
	v_mov_b32_e32 v19, v0
	v_mov_b32_e32 v20, v0
	v_mov_b32_e32 v21, v0
	v_mov_b32_e32 v22, v0
	v_mov_b32_e32 v23, v0
	v_mov_b32_e32 v32, v0
	v_mov_b32_e32 v33, v0
	v_mov_b32_e32 v34, v0
	v_mov_b32_e32 v35, v0
	v_mov_b32_e32 v36, v0
	v_mov_b32_e32 v37, v0
	v_mov_b32_e32 v38, v0
	v_mov_b32_e32 v39, v0
	v_mov_b32_e32 v48, v0
	v_mov_b32_e32 v49, v0
	v_mov_b32_e32 v50, v0
	v_mov_b32_e32 v51, v0
	v_mov_b32_e32 v52, v0
	v_mov_b32_e32 v53, v0
	v_mov_b32_e32 v54, v0
	v_mov_b32_e32 v55, v0
	v_mov_b32_e32 v8, v0
	v_mov_b32_e32 v9, v0
	v_mov_b32_e32 v10, v0
	v_mov_b32_e32 v11, v0
	v_mov_b32_e32 v12, v0
	v_mov_b32_e32 v13, v0
	v_mov_b32_e32 v14, v0
	v_mov_b32_e32 v15, v0
	v_mov_b32_e32 v24, v0
	v_mov_b32_e32 v25, v0
	v_mov_b32_e32 v26, v0
	v_mov_b32_e32 v27, v0
	v_mov_b32_e32 v28, v0
	v_mov_b32_e32 v29, v0
	v_mov_b32_e32 v30, v0
	v_mov_b32_e32 v31, v0
	v_mov_b32_e32 v40, v0
	v_mov_b32_e32 v41, v0
	v_mov_b32_e32 v42, v0
	v_mov_b32_e32 v43, v0
	v_mov_b32_e32 v44, v0
	v_mov_b32_e32 v45, v0
	v_mov_b32_e32 v46, v0
	v_mov_b32_e32 v47, v0
	v_mov_b32_e32 v56, v0
	v_mov_b32_e32 v57, v0
	v_mov_b32_e32 v58, v0
	v_mov_b32_e32 v59, v0
	v_mov_b32_e32 v60, v0
	v_mov_b32_e32 v61, v0
	v_mov_b32_e32 v62, v0
	v_mov_b32_e32 v63, v0
	v_mov_b32_e32 v64, v0
	v_mov_b32_e32 v65, v0
	v_mov_b32_e32 v66, v0
	v_mov_b32_e32 v67, v0
	v_mov_b32_e32 v68, v0
	v_mov_b32_e32 v69, v0
	v_mov_b32_e32 v70, v0
	v_mov_b32_e32 v71, v0
	v_mov_b32_e32 v80, v0
	v_mov_b32_e32 v81, v0
	v_mov_b32_e32 v82, v0
	v_mov_b32_e32 v83, v0
	v_mov_b32_e32 v84, v0
	v_mov_b32_e32 v85, v0
	v_mov_b32_e32 v86, v0
	v_mov_b32_e32 v87, v0
	v_mov_b32_e32 v96, v0
	v_mov_b32_e32 v97, v0
	v_mov_b32_e32 v98, v0
	v_mov_b32_e32 v99, v0
	v_mov_b32_e32 v100, v0
	v_mov_b32_e32 v101, v0
	v_mov_b32_e32 v102, v0
	v_mov_b32_e32 v103, v0
	v_mov_b32_e32 v112, v0
	v_mov_b32_e32 v113, v0
	v_mov_b32_e32 v114, v0
	v_mov_b32_e32 v115, v0
	v_mov_b32_e32 v116, v0
	v_mov_b32_e32 v117, v0
	v_mov_b32_e32 v118, v0
	v_mov_b32_e32 v119, v0
	v_mov_b32_e32 v72, v0
	v_mov_b32_e32 v73, v0
	v_mov_b32_e32 v74, v0
	v_mov_b32_e32 v75, v0
	v_mov_b32_e32 v76, v0
	v_mov_b32_e32 v77, v0
	v_mov_b32_e32 v78, v0
	v_mov_b32_e32 v79, v0
	v_mov_b32_e32 v88, v0
	v_mov_b32_e32 v89, v0
	v_mov_b32_e32 v90, v0
	v_mov_b32_e32 v91, v0
	v_mov_b32_e32 v92, v0
	v_mov_b32_e32 v93, v0
	v_mov_b32_e32 v94, v0
	v_mov_b32_e32 v95, v0
	v_mov_b32_e32 v104, v0
	v_mov_b32_e32 v105, v0
	v_mov_b32_e32 v106, v0
	v_mov_b32_e32 v107, v0
	v_mov_b32_e32 v108, v0
	v_mov_b32_e32 v109, v0
	v_mov_b32_e32 v110, v0
	v_mov_b32_e32 v111, v0
	v_mov_b32_e32 v120, v0
	v_mov_b32_e32 v121, v0
	v_mov_b32_e32 v122, v0
	v_mov_b32_e32 v123, v0
	v_mov_b32_e32 v124, v0
	v_mov_b32_e32 v125, v0
	v_mov_b32_e32 v126, v0
	v_mov_b32_e32 v127, v0
	s_cmp_gt_u32 s97, 3
	s_cbranch_scc1 .Lgprio2
	s_setprio 1

.LBB0_1116:
	s_ashr_i32 s39, s38, 31
	s_lshl_b64 s[40:41], s[38:39], 20
	s_add_u32 s40, s23, s40
	s_addc_u32 s41, s52, s41
	s_and_b64 s[42:43], s[4:5], exec
	s_cselect_b32 s7, s41, s47
	s_cselect_b32 s11, s40, s46
	s_ashr_i32 s37, s36, 31
	s_lshl_b64 s[42:43], s[36:37], 20
	s_add_u32 s42, s53, s42
	s_addc_u32 s43, s54, s43
	s_and_b64 s[50:51], s[4:5], exec
	s_cselect_b32 s37, s43, s49
	s_cselect_b32 s39, s42, s48
	s_add_u32 s46, s46, 0x80080
	s_addc_u32 s47, s47, 0
	s_add_u32 s45, s48, 0x100
	v_mov_b32_e32 v0, 0
	s_addc_u32 s62, s49, 0
	s_mov_b32 s63, -2
	v_mov_b32_e32 v1, v0
	v_mov_b32_e32 v2, v0
	v_mov_b32_e32 v3, v0
	v_mov_b32_e32 v4, v0
	s_waitcnt lgkmcnt(0)
	v_mov_b32_e32 v5, v0
	v_mov_b32_e32 v6, v0
	v_mov_b32_e32 v7, v0
	v_mov_b32_e32 v16, v0
	v_mov_b32_e32 v17, v0
	v_mov_b32_e32 v18, v0
	v_mov_b32_e32 v19, v0
	v_mov_b32_e32 v20, v0
	v_mov_b32_e32 v21, v0
	v_mov_b32_e32 v22, v0
	v_mov_b32_e32 v23, v0
	v_mov_b32_e32 v32, v0
	v_mov_b32_e32 v33, v0
	v_mov_b32_e32 v34, v0
	v_mov_b32_e32 v35, v0
	v_mov_b32_e32 v36, v0
	v_mov_b32_e32 v37, v0
	v_mov_b32_e32 v38, v0
	v_mov_b32_e32 v39, v0
	v_mov_b32_e32 v48, v0
	v_mov_b32_e32 v49, v0
	v_mov_b32_e32 v50, v0
	v_mov_b32_e32 v51, v0
	v_mov_b32_e32 v52, v0
	v_mov_b32_e32 v53, v0
	v_mov_b32_e32 v54, v0
	v_mov_b32_e32 v55, v0
	v_mov_b32_e32 v8, v0
	v_mov_b32_e32 v9, v0
	v_mov_b32_e32 v10, v0
	v_mov_b32_e32 v11, v0
	v_mov_b32_e32 v12, v0
	v_mov_b32_e32 v13, v0
	v_mov_b32_e32 v14, v0
	v_mov_b32_e32 v15, v0
	v_mov_b32_e32 v24, v0
	v_mov_b32_e32 v25, v0
	v_mov_b32_e32 v26, v0
	v_mov_b32_e32 v27, v0
	v_mov_b32_e32 v28, v0
	v_mov_b32_e32 v29, v0
	v_mov_b32_e32 v30, v0
	v_mov_b32_e32 v31, v0
	v_mov_b32_e32 v40, v0
	v_mov_b32_e32 v41, v0
	v_mov_b32_e32 v42, v0
	v_mov_b32_e32 v43, v0
	v_mov_b32_e32 v44, v0
	v_mov_b32_e32 v45, v0
	v_mov_b32_e32 v46, v0
	v_mov_b32_e32 v47, v0
	v_mov_b32_e32 v56, v0
	v_mov_b32_e32 v57, v0
	v_mov_b32_e32 v58, v0
	v_mov_b32_e32 v59, v0
	v_mov_b32_e32 v60, v0
	v_mov_b32_e32 v61, v0
	v_mov_b32_e32 v62, v0
	v_mov_b32_e32 v63, v0
	v_mov_b32_e32 v64, v0
	v_mov_b32_e32 v65, v0
	v_mov_b32_e32 v66, v0
	v_mov_b32_e32 v67, v0
	v_mov_b32_e32 v68, v0
	v_mov_b32_e32 v69, v0
	v_mov_b32_e32 v70, v0
	v_mov_b32_e32 v71, v0
	v_mov_b32_e32 v80, v0
	v_mov_b32_e32 v81, v0
	v_mov_b32_e32 v82, v0
	v_mov_b32_e32 v83, v0
	v_mov_b32_e32 v84, v0
	v_mov_b32_e32 v85, v0
	v_mov_b32_e32 v86, v0
	v_mov_b32_e32 v87, v0
	v_mov_b32_e32 v96, v0
	v_mov_b32_e32 v97, v0
	v_mov_b32_e32 v98, v0
	v_mov_b32_e32 v99, v0
	v_mov_b32_e32 v100, v0
	v_mov_b32_e32 v101, v0
	v_mov_b32_e32 v102, v0
	v_mov_b32_e32 v103, v0
	v_mov_b32_e32 v112, v0
	v_mov_b32_e32 v113, v0
	v_mov_b32_e32 v114, v0
	v_mov_b32_e32 v115, v0
	v_mov_b32_e32 v116, v0
	v_mov_b32_e32 v117, v0
	v_mov_b32_e32 v118, v0
	v_mov_b32_e32 v119, v0
	v_mov_b32_e32 v72, v0
	v_mov_b32_e32 v73, v0
	v_mov_b32_e32 v74, v0
	v_mov_b32_e32 v75, v0
	v_mov_b32_e32 v76, v0
	v_mov_b32_e32 v77, v0
	v_mov_b32_e32 v78, v0
	v_mov_b32_e32 v79, v0
	v_mov_b32_e32 v88, v0
	v_mov_b32_e32 v89, v0
	v_mov_b32_e32 v90, v0
	v_mov_b32_e32 v91, v0
	v_mov_b32_e32 v92, v0
	v_mov_b32_e32 v93, v0
	v_mov_b32_e32 v94, v0
	v_mov_b32_e32 v95, v0
	v_mov_b32_e32 v104, v0
	v_mov_b32_e32 v105, v0
	v_mov_b32_e32 v106, v0
	v_mov_b32_e32 v107, v0
	v_mov_b32_e32 v108, v0
	v_mov_b32_e32 v109, v0
	v_mov_b32_e32 v110, v0
	v_mov_b32_e32 v111, v0
	v_mov_b32_e32 v120, v0
	v_mov_b32_e32 v121, v0
	v_mov_b32_e32 v122, v0
	v_mov_b32_e32 v123, v0
	v_mov_b32_e32 v124, v0
	v_mov_b32_e32 v125, v0
	v_mov_b32_e32 v126, v0
	v_mov_b32_e32 v127, v0
	s_cmp_gt_u32 s97, 3
	s_cbranch_scc1 .Lgprio3
	s_setprio 1

.LBB0_1239:
	s_ashr_i32 s29, s28, 31
	s_lshl_b64 s[30:31], s[28:29], 20
	s_add_u32 s30, s23, s30
	s_addc_u32 s31, s26, s31
	s_and_b64 s[34:35], s[2:3], exec
	s_cselect_b32 s29, s31, s39
	s_cselect_b32 s57, s30, s38
	s_ashr_i32 s19, s18, 31
	s_lshl_b64 s[34:35], s[18:19], 20
	s_add_u32 s34, s27, s34
	s_addc_u32 s35, s46, s35
	s_and_b64 s[42:43], s[2:3], exec
	s_cselect_b32 s19, s35, s41
	s_cselect_b32 s58, s34, s40
	s_add_u32 s59, s40, 0x100
	v_mov_b32_e32 v0, 0
	s_addc_u32 s60, s41, 0
	s_mov_b32 s61, -2
	v_mov_b32_e32 v1, v0
	v_mov_b32_e32 v2, v0
	v_mov_b32_e32 v3, v0
	v_mov_b32_e32 v4, v0
	v_mov_b32_e32 v5, v0
	v_mov_b32_e32 v6, v0
	v_mov_b32_e32 v7, v0
	v_mov_b32_e32 v16, v0
	v_mov_b32_e32 v17, v0
	v_mov_b32_e32 v18, v0
	v_mov_b32_e32 v19, v0
	v_mov_b32_e32 v20, v0
	v_mov_b32_e32 v21, v0
	v_mov_b32_e32 v22, v0
	v_mov_b32_e32 v23, v0
	v_mov_b32_e32 v32, v0
	v_mov_b32_e32 v33, v0
	v_mov_b32_e32 v34, v0
	v_mov_b32_e32 v35, v0
	v_mov_b32_e32 v36, v0
	v_mov_b32_e32 v37, v0
	v_mov_b32_e32 v38, v0
	v_mov_b32_e32 v39, v0
	v_mov_b32_e32 v48, v0
	v_mov_b32_e32 v49, v0
	v_mov_b32_e32 v50, v0
	v_mov_b32_e32 v51, v0
	v_mov_b32_e32 v52, v0
	v_mov_b32_e32 v53, v0
	v_mov_b32_e32 v54, v0
	v_mov_b32_e32 v55, v0
	v_mov_b32_e32 v8, v0
	v_mov_b32_e32 v9, v0
	v_mov_b32_e32 v10, v0
	v_mov_b32_e32 v11, v0
	v_mov_b32_e32 v12, v0
	v_mov_b32_e32 v13, v0
	v_mov_b32_e32 v14, v0
	v_mov_b32_e32 v15, v0
	v_mov_b32_e32 v24, v0
	v_mov_b32_e32 v25, v0
	v_mov_b32_e32 v26, v0
	v_mov_b32_e32 v27, v0
	v_mov_b32_e32 v28, v0
	v_mov_b32_e32 v29, v0
	v_mov_b32_e32 v30, v0
	v_mov_b32_e32 v31, v0
	v_mov_b32_e32 v40, v0
	v_mov_b32_e32 v41, v0
	v_mov_b32_e32 v42, v0
	v_mov_b32_e32 v43, v0
	v_mov_b32_e32 v44, v0
	v_mov_b32_e32 v45, v0
	v_mov_b32_e32 v46, v0
	v_mov_b32_e32 v47, v0
	v_mov_b32_e32 v56, v0
	v_mov_b32_e32 v57, v0
	v_mov_b32_e32 v58, v0
	v_mov_b32_e32 v59, v0
	v_mov_b32_e32 v60, v0
	v_mov_b32_e32 v61, v0
	v_mov_b32_e32 v62, v0
	v_mov_b32_e32 v63, v0
	v_mov_b32_e32 v64, v0
	v_mov_b32_e32 v65, v0
	v_mov_b32_e32 v66, v0
	v_mov_b32_e32 v67, v0
	v_mov_b32_e32 v68, v0
	v_mov_b32_e32 v69, v0
	v_mov_b32_e32 v70, v0
	v_mov_b32_e32 v71, v0
	v_mov_b32_e32 v80, v0
	v_mov_b32_e32 v81, v0
	v_mov_b32_e32 v82, v0
	v_mov_b32_e32 v83, v0
	v_mov_b32_e32 v84, v0
	v_mov_b32_e32 v85, v0
	v_mov_b32_e32 v86, v0
	v_mov_b32_e32 v87, v0
	v_mov_b32_e32 v96, v0
	v_mov_b32_e32 v97, v0
	v_mov_b32_e32 v98, v0
	v_mov_b32_e32 v99, v0
	v_mov_b32_e32 v100, v0
	v_mov_b32_e32 v101, v0
	v_mov_b32_e32 v102, v0
	v_mov_b32_e32 v103, v0
	v_mov_b32_e32 v112, v0
	v_mov_b32_e32 v113, v0
	v_mov_b32_e32 v114, v0
	v_mov_b32_e32 v115, v0
	v_mov_b32_e32 v116, v0
	v_mov_b32_e32 v117, v0
	v_mov_b32_e32 v118, v0
	v_mov_b32_e32 v119, v0
	v_mov_b32_e32 v72, v0
	v_mov_b32_e32 v73, v0
	v_mov_b32_e32 v74, v0
	v_mov_b32_e32 v75, v0
	v_mov_b32_e32 v76, v0
	v_mov_b32_e32 v77, v0
	v_mov_b32_e32 v78, v0
	v_mov_b32_e32 v79, v0
	v_mov_b32_e32 v88, v0
	v_mov_b32_e32 v89, v0
	v_mov_b32_e32 v90, v0
	v_mov_b32_e32 v91, v0
	v_mov_b32_e32 v92, v0
	v_mov_b32_e32 v93, v0
	v_mov_b32_e32 v94, v0
	v_mov_b32_e32 v95, v0
	v_mov_b32_e32 v104, v0
	v_mov_b32_e32 v105, v0
	v_mov_b32_e32 v106, v0
	v_mov_b32_e32 v107, v0
	v_mov_b32_e32 v108, v0
	v_mov_b32_e32 v109, v0
	v_mov_b32_e32 v110, v0
	v_mov_b32_e32 v111, v0
	v_mov_b32_e32 v120, v0
	v_mov_b32_e32 v121, v0
	v_mov_b32_e32 v122, v0
	v_mov_b32_e32 v123, v0
	v_mov_b32_e32 v124, v0
	v_mov_b32_e32 v125, v0
	v_mov_b32_e32 v126, v0
	v_mov_b32_e32 v127, v0
	s_cmp_gt_u32 s97, 3
	s_cbranch_scc1 .Lgprio4
	s_setprio 1

.LBB0_1326:
	s_add_u32 s53, s34, 0x100
	v_mov_b32_e32 v0, 0
	s_addc_u32 s54, s35, 0
	s_mov_b32 s55, -2
	v_mov_b32_e32 v1, v0
	v_mov_b32_e32 v2, v0
	v_mov_b32_e32 v3, v0
	v_mov_b32_e32 v4, v0
	v_mov_b32_e32 v5, v0
	v_mov_b32_e32 v6, v0
	v_mov_b32_e32 v7, v0
	v_mov_b32_e32 v16, v0
	v_mov_b32_e32 v17, v0
	v_mov_b32_e32 v18, v0
	v_mov_b32_e32 v19, v0
	v_mov_b32_e32 v20, v0
	v_mov_b32_e32 v21, v0
	v_mov_b32_e32 v22, v0
	v_mov_b32_e32 v23, v0
	v_mov_b32_e32 v32, v0
	v_mov_b32_e32 v33, v0
	v_mov_b32_e32 v34, v0
	v_mov_b32_e32 v35, v0
	v_mov_b32_e32 v36, v0
	v_mov_b32_e32 v37, v0
	v_mov_b32_e32 v38, v0
	v_mov_b32_e32 v39, v0
	v_mov_b32_e32 v48, v0
	v_mov_b32_e32 v49, v0
	v_mov_b32_e32 v50, v0
	v_mov_b32_e32 v51, v0
	v_mov_b32_e32 v52, v0
	v_mov_b32_e32 v53, v0
	v_mov_b32_e32 v54, v0
	v_mov_b32_e32 v55, v0
	v_mov_b32_e32 v8, v0
	v_mov_b32_e32 v9, v0
	v_mov_b32_e32 v10, v0
	v_mov_b32_e32 v11, v0
	v_mov_b32_e32 v12, v0
	v_mov_b32_e32 v13, v0
	v_mov_b32_e32 v14, v0
	v_mov_b32_e32 v15, v0
	v_mov_b32_e32 v24, v0
	v_mov_b32_e32 v25, v0
	v_mov_b32_e32 v26, v0
	v_mov_b32_e32 v27, v0
	v_mov_b32_e32 v28, v0
	v_mov_b32_e32 v29, v0
	v_mov_b32_e32 v30, v0
	v_mov_b32_e32 v31, v0
	v_mov_b32_e32 v40, v0
	v_mov_b32_e32 v41, v0
	v_mov_b32_e32 v42, v0
	v_mov_b32_e32 v43, v0
	v_mov_b32_e32 v44, v0
	v_mov_b32_e32 v45, v0
	v_mov_b32_e32 v46, v0
	v_mov_b32_e32 v47, v0
	v_mov_b32_e32 v56, v0
	v_mov_b32_e32 v57, v0
	v_mov_b32_e32 v58, v0
	v_mov_b32_e32 v59, v0
	v_mov_b32_e32 v60, v0
	v_mov_b32_e32 v61, v0
	v_mov_b32_e32 v62, v0
	v_mov_b32_e32 v63, v0
	v_mov_b32_e32 v64, v0
	v_mov_b32_e32 v65, v0
	v_mov_b32_e32 v66, v0
	v_mov_b32_e32 v67, v0
	v_mov_b32_e32 v68, v0
	v_mov_b32_e32 v69, v0
	v_mov_b32_e32 v70, v0
	v_mov_b32_e32 v71, v0
	v_mov_b32_e32 v80, v0
	v_mov_b32_e32 v81, v0
	v_mov_b32_e32 v82, v0
	v_mov_b32_e32 v83, v0
	v_mov_b32_e32 v84, v0
	v_mov_b32_e32 v85, v0
	v_mov_b32_e32 v86, v0
	v_mov_b32_e32 v87, v0
	v_mov_b32_e32 v96, v0
	v_mov_b32_e32 v97, v0
	v_mov_b32_e32 v98, v0
	v_mov_b32_e32 v99, v0
	v_mov_b32_e32 v100, v0
	v_mov_b32_e32 v101, v0
	v_mov_b32_e32 v102, v0
	v_mov_b32_e32 v103, v0
	v_mov_b32_e32 v112, v0
	v_mov_b32_e32 v113, v0
	v_mov_b32_e32 v114, v0
	v_mov_b32_e32 v115, v0
	v_mov_b32_e32 v116, v0
	v_mov_b32_e32 v117, v0
	v_mov_b32_e32 v118, v0
	v_mov_b32_e32 v119, v0
	v_mov_b32_e32 v72, v0
	v_mov_b32_e32 v73, v0
	v_mov_b32_e32 v74, v0
	v_mov_b32_e32 v75, v0
	v_mov_b32_e32 v76, v0
	v_mov_b32_e32 v77, v0
	v_mov_b32_e32 v78, v0
	v_mov_b32_e32 v79, v0
	v_mov_b32_e32 v88, v0
	v_mov_b32_e32 v89, v0
	v_mov_b32_e32 v90, v0
	v_mov_b32_e32 v91, v0
	v_mov_b32_e32 v92, v0
	v_mov_b32_e32 v93, v0
	v_mov_b32_e32 v94, v0
	v_mov_b32_e32 v95, v0
	v_mov_b32_e32 v104, v0
	v_mov_b32_e32 v105, v0
	v_mov_b32_e32 v106, v0
	v_mov_b32_e32 v107, v0
	v_mov_b32_e32 v108, v0
	v_mov_b32_e32 v109, v0
	v_mov_b32_e32 v110, v0
	v_mov_b32_e32 v111, v0
	v_mov_b32_e32 v120, v0
	v_mov_b32_e32 v121, v0
	v_mov_b32_e32 v122, v0
	v_mov_b32_e32 v123, v0
	v_mov_b32_e32 v124, v0
	v_mov_b32_e32 v125, v0
	v_mov_b32_e32 v126, v0
	v_mov_b32_e32 v127, v0
	s_cmp_gt_u32 s97, 3
	s_cbranch_scc1 .Lgprio5
	s_setprio 1
